# K-loop staging: M0 write ahead of the address add (12 s_nop removed)
# baseline (speedup 1.0000x reference)
.LBB0_149:
	s_add_i32 s34, s19, -2
	s_add_u32 s92, s92, 0x80
	s_addc_u32 s93, s93, 0
	s_add_u32 s96, s94, 0x100
	s_addc_u32 s97, s95, 0
	s_mov_b32 s94, 0
	s_cmp_lt_u32 s59, 2
	s_cbranch_scc1 .Lkloop_zero
	s_add_i32 vcc_lo, s94, 2
	s_add_u32 s82, s92, 0x80
	s_addc_u32 s83, s93, 0
	s_add_i32 vcc_hi, 0, 0x10000
	s_cmp_eq_u32 s34, s94
	s_cselect_b32 s95, s89, s83
	s_cselect_b32 s94, s88, s82
	v_add_u32_e32 v136, vcc_hi, v176
	s_cselect_b32 s83, s91, s97
	s_cselect_b32 s82, s90, s96
	s_add_i32 s7, 0, 0x14000
	s_waitcnt lgkmcnt(0)
	ds_read_b128 v[128:131], v136
	ds_read_b128 v[132:135], v136 offset:1024
	ds_read_b128 v[152:155], v136 offset:2048
	ds_read_b128 v[156:159], v136 offset:3072
	v_add_u32_e32 v136, s7, v176
	ds_read_b128 v[180:183], v136
	ds_read_b128 v[184:187], v136 offset:1024
	ds_read_b128 v[188:191], v136 offset:2048
	ds_read_b128 v[192:195], v136 offset:3072
	v_lshl_add_u64 v[160:161], s[92:93], 0, v[148:149]
	s_add_i32 m0, s52, 0xc000
	ds_read_b128 v[196:199], v178
	ds_read_b128 v[200:203], v178 offset:1024
	ds_read_b128 v[204:207], v178 offset:2048
	ds_read_b128 v[208:211], v178 offset:3072
	ds_read_b128 v[212:215], v178 offset:4096
	ds_read_b128 v[216:219], v178 offset:5120
	ds_read_b128 v[220:223], v178 offset:6144
	ds_read_b128 v[224:227], v178 offset:7168
	global_load_lds_dwordx4 v[160:161], off
	s_add_i32 m0, s52, 0xe000
	v_lshl_add_u64 v[160:161], s[92:93], 0, v[150:151]
	global_load_lds_dwordx4 v[160:161], off
	s_waitcnt vmcnt(24)
	s_waitcnt lgkmcnt(0)
	s_barrier
	s_setprio 1
	s_waitcnt lgkmcnt(0)
	v_mfma_f32_16x16x32_bf16 v[124:127], v[128:131], v[196:199], 0
	v_mfma_f32_16x16x32_bf16 v[120:123], v[152:155], v[196:199], 0
	v_mfma_f32_16x16x32_bf16 v[108:111], v[128:131], v[204:207], 0
	v_mfma_f32_16x16x32_bf16 v[104:107], v[152:155], v[204:207], 0
	v_mfma_f32_16x16x32_bf16 v[92:95], v[128:131], v[212:215], 0
	v_mfma_f32_16x16x32_bf16 v[88:91], v[152:155], v[212:215], 0
	v_mfma_f32_16x16x32_bf16 v[76:79], v[128:131], v[220:223], 0
	v_mfma_f32_16x16x32_bf16 v[72:75], v[152:155], v[220:223], 0
	v_mfma_f32_16x16x32_bf16 v[124:127], v[132:135], v[200:203], v[124:127]
	v_mfma_f32_16x16x32_bf16 v[120:123], v[156:159], v[200:203], v[120:123]
	v_mfma_f32_16x16x32_bf16 v[108:111], v[132:135], v[208:211], v[108:111]
	v_mfma_f32_16x16x32_bf16 v[104:107], v[156:159], v[208:211], v[104:107]
	v_mfma_f32_16x16x32_bf16 v[92:95], v[132:135], v[216:219], v[92:95]
	v_mfma_f32_16x16x32_bf16 v[88:91], v[156:159], v[216:219], v[88:91]
	v_mfma_f32_16x16x32_bf16 v[76:79], v[132:135], v[224:227], v[76:79]
	v_mfma_f32_16x16x32_bf16 v[72:75], v[156:159], v[224:227], v[72:75]
	s_setprio 0
	s_setprio 1
	v_mfma_f32_16x16x32_bf16 v[116:119], v[180:183], v[196:199], 0
	v_mfma_f32_16x16x32_bf16 v[112:115], v[188:191], v[196:199], 0
	v_mfma_f32_16x16x32_bf16 v[100:103], v[180:183], v[204:207], 0
	v_mfma_f32_16x16x32_bf16 v[96:99], v[188:191], v[204:207], 0
	v_mfma_f32_16x16x32_bf16 v[84:87], v[180:183], v[212:215], 0
	v_mfma_f32_16x16x32_bf16 v[80:83], v[188:191], v[212:215], 0
	v_mfma_f32_16x16x32_bf16 v[68:71], v[180:183], v[220:223], 0
	v_mfma_f32_16x16x32_bf16 v[64:67], v[188:191], v[220:223], 0
	v_mfma_f32_16x16x32_bf16 v[116:119], v[184:187], v[200:203], v[116:119]
	v_mfma_f32_16x16x32_bf16 v[112:115], v[192:195], v[200:203], v[112:115]
	v_mfma_f32_16x16x32_bf16 v[100:103], v[184:187], v[208:211], v[100:103]
	v_mfma_f32_16x16x32_bf16 v[96:99], v[192:195], v[208:211], v[96:99]
	v_mfma_f32_16x16x32_bf16 v[84:87], v[184:187], v[216:219], v[84:87]
	v_mfma_f32_16x16x32_bf16 v[80:83], v[192:195], v[216:219], v[80:83]
	v_mfma_f32_16x16x32_bf16 v[68:71], v[184:187], v[224:227], v[68:71]
	v_mfma_f32_16x16x32_bf16 v[64:67], v[192:195], v[224:227], v[64:67]
	s_setprio 0
	s_barrier
	s_add_i32 vcc_hi, vcc_hi, s51
	v_lshl_add_u64 v[160:161], s[82:83], 0, v[140:141]
	s_mov_b32 m0, vcc_hi
	ds_read_b128 v[196:199], v178 offset:16384
	ds_read_b128 v[200:203], v178 offset:17408
	ds_read_b128 v[204:207], v178 offset:18432
	ds_read_b128 v[208:211], v178 offset:19456
	ds_read_b128 v[212:215], v178 offset:20480
	ds_read_b128 v[216:219], v178 offset:21504
	ds_read_b128 v[220:223], v178 offset:22528
	ds_read_b128 v[224:227], v178 offset:23552
	global_load_lds_dwordx4 v[160:161], off
	s_add_i32 m0, vcc_hi, 0x2000
	v_lshl_add_u64 v[228:229], s[82:83], 0, v[144:145]
	s_add_u32 s82, s82, s2
	s_addc_u32 s83, s83, s3
	s_add_i32 s7, s7, s51
	global_load_lds_dwordx4 v[228:229], off
	v_lshl_add_u64 v[230:231], s[82:83], 0, v[140:141]
	s_mov_b32 m0, s7
	v_lshl_add_u64 v[232:233], s[82:83], 0, v[144:145]
	global_load_lds_dwordx4 v[230:231], off
	s_add_i32 m0, s7, 0x2000
	v_lshl_add_u64 v[234:235], s[94:95], 0, v[138:139]
	global_load_lds_dwordx4 v[232:233], off
	s_mov_b32 m0, s52
	v_lshl_add_u64 v[236:237], s[94:95], 0, v[142:143]
	global_load_lds_dwordx4 v[234:235], off
	s_mov_b32 m0, s53
	s_nop 0
	global_load_lds_dwordx4 v[236:237], off
	s_waitcnt vmcnt(24)
	s_waitcnt lgkmcnt(0)
	s_barrier
	s_setprio 1
	s_waitcnt lgkmcnt(0)
	v_mfma_f32_16x16x32_bf16 v[60:63], v[128:131], v[196:199], 0
	v_mfma_f32_16x16x32_bf16 v[56:59], v[152:155], v[196:199], 0
	v_mfma_f32_16x16x32_bf16 v[44:47], v[128:131], v[204:207], 0
	v_mfma_f32_16x16x32_bf16 v[40:43], v[152:155], v[204:207], 0
	v_mfma_f32_16x16x32_bf16 v[28:31], v[128:131], v[212:215], 0
	v_mfma_f32_16x16x32_bf16 v[24:27], v[152:155], v[212:215], 0
	v_mfma_f32_16x16x32_bf16 v[12:15], v[128:131], v[220:223], 0
	v_mfma_f32_16x16x32_bf16 v[8:11], v[152:155], v[220:223], 0
	v_mfma_f32_16x16x32_bf16 v[60:63], v[132:135], v[200:203], v[60:63]
	v_mfma_f32_16x16x32_bf16 v[56:59], v[156:159], v[200:203], v[56:59]
	v_mfma_f32_16x16x32_bf16 v[44:47], v[132:135], v[208:211], v[44:47]
	v_mfma_f32_16x16x32_bf16 v[40:43], v[156:159], v[208:211], v[40:43]
	v_mfma_f32_16x16x32_bf16 v[28:31], v[132:135], v[216:219], v[28:31]
	v_mfma_f32_16x16x32_bf16 v[24:27], v[156:159], v[216:219], v[24:27]
	v_mfma_f32_16x16x32_bf16 v[12:15], v[132:135], v[224:227], v[12:15]
	v_mfma_f32_16x16x32_bf16 v[8:11], v[156:159], v[224:227], v[8:11]
	s_setprio 0
	s_setprio 1
	v_mfma_f32_16x16x32_bf16 v[52:55], v[180:183], v[196:199], 0
	v_mfma_f32_16x16x32_bf16 v[48:51], v[188:191], v[196:199], 0
	v_mfma_f32_16x16x32_bf16 v[36:39], v[180:183], v[204:207], 0
	v_mfma_f32_16x16x32_bf16 v[32:35], v[188:191], v[204:207], 0
	v_mfma_f32_16x16x32_bf16 v[20:23], v[180:183], v[212:215], 0
	v_mfma_f32_16x16x32_bf16 v[16:19], v[188:191], v[212:215], 0
	v_mfma_f32_16x16x32_bf16 v[4:7], v[180:183], v[220:223], 0
	v_mfma_f32_16x16x32_bf16 v[0:3], v[188:191], v[220:223], 0
	v_mfma_f32_16x16x32_bf16 v[52:55], v[184:187], v[200:203], v[52:55]
	v_mfma_f32_16x16x32_bf16 v[48:51], v[192:195], v[200:203], v[48:51]
	v_mfma_f32_16x16x32_bf16 v[36:39], v[184:187], v[208:211], v[36:39]
	v_mfma_f32_16x16x32_bf16 v[32:35], v[192:195], v[208:211], v[32:35]
	v_mfma_f32_16x16x32_bf16 v[20:23], v[184:187], v[216:219], v[20:23]
	v_mfma_f32_16x16x32_bf16 v[16:19], v[192:195], v[216:219], v[16:19]
	v_mfma_f32_16x16x32_bf16 v[4:7], v[184:187], v[224:227], v[4:7]
	v_mfma_f32_16x16x32_bf16 v[0:3], v[192:195], v[224:227], v[0:3]
	s_setprio 0
	s_barrier
	s_add_i32 s7, 0, 0x18000
	v_add_u32_e32 v136, s7, v176
	s_add_i32 vcc_hi, 0, 0x1c000
	ds_read_b128 v[128:131], v136
	ds_read_b128 v[132:135], v136 offset:1024
	ds_read_b128 v[152:155], v136 offset:2048
	ds_read_b128 v[156:159], v136 offset:3072
	v_add_u32_e32 v136, vcc_hi, v176
	ds_read_b128 v[180:183], v136
	ds_read_b128 v[184:187], v136 offset:1024
	ds_read_b128 v[188:191], v136 offset:2048
	ds_read_b128 v[192:195], v136 offset:3072
	s_add_u32 s82, s94, s2
	s_addc_u32 s83, s95, s3
	s_mov_b32 m0, s54
	v_lshl_add_u64 v[238:239], s[82:83], 0, v[138:139]
	ds_read_b128 v[196:199], v178 offset:32768
	ds_read_b128 v[200:203], v178 offset:33792
	ds_read_b128 v[204:207], v178 offset:34816
	ds_read_b128 v[208:211], v178 offset:35840
	ds_read_b128 v[212:215], v178 offset:36864
	ds_read_b128 v[216:219], v178 offset:37888
	ds_read_b128 v[220:223], v178 offset:38912
	ds_read_b128 v[224:227], v178 offset:39936
	global_load_lds_dwordx4 v[238:239], off
	s_mov_b32 m0, s55
	v_lshl_add_u64 v[238:239], s[82:83], 0, v[142:143]
	global_load_lds_dwordx4 v[238:239], off
	s_waitcnt vmcnt(8)
	s_waitcnt lgkmcnt(0)
	s_barrier
	s_setprio 1
	s_waitcnt lgkmcnt(0)
	v_mfma_f32_16x16x32_bf16 v[124:127], v[128:131], v[196:199], v[124:127]
	v_mfma_f32_16x16x32_bf16 v[120:123], v[152:155], v[196:199], v[120:123]
	v_mfma_f32_16x16x32_bf16 v[108:111], v[128:131], v[204:207], v[108:111]
	v_mfma_f32_16x16x32_bf16 v[104:107], v[152:155], v[204:207], v[104:107]
	v_mfma_f32_16x16x32_bf16 v[92:95], v[128:131], v[212:215], v[92:95]
	v_mfma_f32_16x16x32_bf16 v[88:91], v[152:155], v[212:215], v[88:91]
	v_mfma_f32_16x16x32_bf16 v[76:79], v[128:131], v[220:223], v[76:79]
	v_mfma_f32_16x16x32_bf16 v[72:75], v[152:155], v[220:223], v[72:75]
	v_mfma_f32_16x16x32_bf16 v[124:127], v[132:135], v[200:203], v[124:127]
	v_mfma_f32_16x16x32_bf16 v[120:123], v[156:159], v[200:203], v[120:123]
	v_mfma_f32_16x16x32_bf16 v[108:111], v[132:135], v[208:211], v[108:111]
	v_mfma_f32_16x16x32_bf16 v[104:107], v[156:159], v[208:211], v[104:107]
	v_mfma_f32_16x16x32_bf16 v[92:95], v[132:135], v[216:219], v[92:95]
	v_mfma_f32_16x16x32_bf16 v[88:91], v[156:159], v[216:219], v[88:91]
	v_mfma_f32_16x16x32_bf16 v[76:79], v[132:135], v[224:227], v[76:79]
	v_mfma_f32_16x16x32_bf16 v[72:75], v[156:159], v[224:227], v[72:75]
	s_setprio 0
	s_setprio 1
	v_mfma_f32_16x16x32_bf16 v[116:119], v[180:183], v[196:199], v[116:119]
	v_mfma_f32_16x16x32_bf16 v[112:115], v[188:191], v[196:199], v[112:115]
	v_mfma_f32_16x16x32_bf16 v[100:103], v[180:183], v[204:207], v[100:103]
	v_mfma_f32_16x16x32_bf16 v[96:99], v[188:191], v[204:207], v[96:99]
	v_mfma_f32_16x16x32_bf16 v[84:87], v[180:183], v[212:215], v[84:87]
	v_mfma_f32_16x16x32_bf16 v[80:83], v[188:191], v[212:215], v[80:83]
	v_mfma_f32_16x16x32_bf16 v[68:71], v[180:183], v[220:223], v[68:71]
	v_mfma_f32_16x16x32_bf16 v[64:67], v[188:191], v[220:223], v[64:67]
	v_mfma_f32_16x16x32_bf16 v[116:119], v[184:187], v[200:203], v[116:119]
	v_mfma_f32_16x16x32_bf16 v[112:115], v[192:195], v[200:203], v[112:115]
	v_mfma_f32_16x16x32_bf16 v[100:103], v[184:187], v[208:211], v[100:103]
	v_mfma_f32_16x16x32_bf16 v[96:99], v[192:195], v[208:211], v[96:99]
	v_mfma_f32_16x16x32_bf16 v[84:87], v[184:187], v[216:219], v[84:87]
	v_mfma_f32_16x16x32_bf16 v[80:83], v[192:195], v[216:219], v[80:83]
	v_mfma_f32_16x16x32_bf16 v[68:71], v[184:187], v[224:227], v[68:71]
	v_mfma_f32_16x16x32_bf16 v[64:67], v[192:195], v[224:227], v[64:67]
	s_setprio 0
	s_barrier
	s_add_i32 s7, s7, s51
	v_lshl_add_u64 v[160:161], v[160:161], 0, s[26:27]
	s_mov_b32 m0, s7
	ds_read_b128 v[196:199], v178 offset:49152
	ds_read_b128 v[200:203], v178 offset:50176
	ds_read_b128 v[204:207], v178 offset:51200
	ds_read_b128 v[208:211], v178 offset:52224
	ds_read_b128 v[212:215], v178 offset:53248
	ds_read_b128 v[216:219], v178 offset:54272
	ds_read_b128 v[220:223], v178 offset:55296
	ds_read_b128 v[224:227], v178 offset:56320
	global_load_lds_dwordx4 v[160:161], off
	v_lshl_add_u64 v[160:161], v[228:229], 0, s[26:27]
	s_add_i32 m0, s7, 0x2000
	s_add_i32 s7, vcc_hi, s51
	global_load_lds_dwordx4 v[160:161], off
	s_mov_b32 m0, s7
	v_lshl_add_u64 v[160:161], v[230:231], 0, s[26:27]
	global_load_lds_dwordx4 v[160:161], off
	s_add_i32 m0, s7, 0x2000
	v_lshl_add_u64 v[160:161], v[232:233], 0, s[26:27]
	global_load_lds_dwordx4 v[160:161], off
	s_mov_b32 m0, s57
	v_lshl_add_u64 v[160:161], v[234:235], 0, s[26:27]
	global_load_lds_dwordx4 v[160:161], off
	s_mov_b32 m0, s58
	v_lshl_add_u64 v[160:161], v[236:237], 0, s[26:27]
	global_load_lds_dwordx4 v[160:161], off
	s_waitcnt vmcnt(8)
	s_waitcnt lgkmcnt(0)
	s_barrier
	s_setprio 1
	s_waitcnt lgkmcnt(0)
	v_mfma_f32_16x16x32_bf16 v[60:63], v[128:131], v[196:199], v[60:63]
	v_mfma_f32_16x16x32_bf16 v[56:59], v[152:155], v[196:199], v[56:59]
	v_mfma_f32_16x16x32_bf16 v[44:47], v[128:131], v[204:207], v[44:47]
	v_mfma_f32_16x16x32_bf16 v[40:43], v[152:155], v[204:207], v[40:43]
	v_mfma_f32_16x16x32_bf16 v[28:31], v[128:131], v[212:215], v[28:31]
	v_mfma_f32_16x16x32_bf16 v[24:27], v[152:155], v[212:215], v[24:27]
	v_mfma_f32_16x16x32_bf16 v[12:15], v[128:131], v[220:223], v[12:15]
	v_mfma_f32_16x16x32_bf16 v[8:11], v[152:155], v[220:223], v[8:11]
	v_mfma_f32_16x16x32_bf16 v[60:63], v[132:135], v[200:203], v[60:63]
	v_mfma_f32_16x16x32_bf16 v[56:59], v[156:159], v[200:203], v[56:59]
	v_mfma_f32_16x16x32_bf16 v[44:47], v[132:135], v[208:211], v[44:47]
	v_mfma_f32_16x16x32_bf16 v[40:43], v[156:159], v[208:211], v[40:43]
	v_mfma_f32_16x16x32_bf16 v[28:31], v[132:135], v[216:219], v[28:31]
	v_mfma_f32_16x16x32_bf16 v[24:27], v[156:159], v[216:219], v[24:27]
	v_mfma_f32_16x16x32_bf16 v[12:15], v[132:135], v[224:227], v[12:15]
	v_mfma_f32_16x16x32_bf16 v[8:11], v[156:159], v[224:227], v[8:11]
	s_setprio 0
	s_setprio 1
	v_mfma_f32_16x16x32_bf16 v[52:55], v[180:183], v[196:199], v[52:55]
	v_mfma_f32_16x16x32_bf16 v[48:51], v[188:191], v[196:199], v[48:51]
	v_mfma_f32_16x16x32_bf16 v[36:39], v[180:183], v[204:207], v[36:39]
	v_mfma_f32_16x16x32_bf16 v[32:35], v[188:191], v[204:207], v[32:35]
	v_mfma_f32_16x16x32_bf16 v[20:23], v[180:183], v[212:215], v[20:23]
	v_mfma_f32_16x16x32_bf16 v[16:19], v[188:191], v[212:215], v[16:19]
	v_mfma_f32_16x16x32_bf16 v[4:7], v[180:183], v[220:223], v[4:7]
	v_mfma_f32_16x16x32_bf16 v[0:3], v[188:191], v[220:223], v[0:3]
	v_mfma_f32_16x16x32_bf16 v[52:55], v[184:187], v[200:203], v[52:55]
	v_mfma_f32_16x16x32_bf16 v[48:51], v[192:195], v[200:203], v[48:51]
	v_mfma_f32_16x16x32_bf16 v[36:39], v[184:187], v[208:211], v[36:39]
	v_mfma_f32_16x16x32_bf16 v[32:35], v[192:195], v[208:211], v[32:35]
	v_mfma_f32_16x16x32_bf16 v[20:23], v[184:187], v[216:219], v[20:23]
	v_mfma_f32_16x16x32_bf16 v[16:19], v[192:195], v[216:219], v[16:19]
	v_mfma_f32_16x16x32_bf16 v[4:7], v[184:187], v[224:227], v[4:7]
	v_mfma_f32_16x16x32_bf16 v[0:3], v[192:195], v[224:227], v[0:3]
	s_setprio 0
	s_barrier
	s_add_u32 s92, s92, 0x100
	s_addc_u32 s93, s93, 0
	s_add_u32 s96, s96, 0x100
	s_addc_u32 s97, s97, 0
	s_cmp_ge_u32 vcc_lo, s19
	s_mov_b32 s94, vcc_lo
	s_cbranch_scc0 .LBB0_150
	s_branch .Lkloop_done

.LBB0_150:
	s_add_i32 vcc_lo, s94, 2
	s_add_u32 s82, s92, 0x80
	s_addc_u32 s83, s93, 0
	s_add_i32 vcc_hi, 0, 0x10000
	s_cmp_eq_u32 s34, s94
	s_cselect_b32 s95, s89, s83
	s_cselect_b32 s94, s88, s82
	v_add_u32_e32 v136, vcc_hi, v176
	s_cselect_b32 s83, s91, s97
	s_cselect_b32 s82, s90, s96
	s_add_i32 s7, 0, 0x14000
	s_waitcnt lgkmcnt(0)
	ds_read_b128 v[128:131], v136
	ds_read_b128 v[132:135], v136 offset:1024
	ds_read_b128 v[152:155], v136 offset:2048
	ds_read_b128 v[156:159], v136 offset:3072
	v_add_u32_e32 v136, s7, v176
	ds_read_b128 v[180:183], v136
	ds_read_b128 v[184:187], v136 offset:1024
	ds_read_b128 v[188:191], v136 offset:2048
	ds_read_b128 v[192:195], v136 offset:3072
	v_lshl_add_u64 v[160:161], s[92:93], 0, v[148:149]
	s_add_i32 m0, s52, 0xc000
	ds_read_b128 v[196:199], v178
	ds_read_b128 v[200:203], v178 offset:1024
	ds_read_b128 v[204:207], v178 offset:2048
	ds_read_b128 v[208:211], v178 offset:3072
	ds_read_b128 v[212:215], v178 offset:4096
	ds_read_b128 v[216:219], v178 offset:5120
	ds_read_b128 v[220:223], v178 offset:6144
	ds_read_b128 v[224:227], v178 offset:7168
	global_load_lds_dwordx4 v[160:161], off
	s_add_i32 m0, s52, 0xe000
	v_lshl_add_u64 v[160:161], s[92:93], 0, v[150:151]
	global_load_lds_dwordx4 v[160:161], off
	s_waitcnt vmcnt(8)
	s_waitcnt lgkmcnt(0)
	s_barrier
	s_setprio 1
	s_waitcnt lgkmcnt(0)
	v_mfma_f32_16x16x32_bf16 v[124:127], v[128:131], v[196:199], v[124:127]
	v_mfma_f32_16x16x32_bf16 v[120:123], v[152:155], v[196:199], v[120:123]
	v_mfma_f32_16x16x32_bf16 v[108:111], v[128:131], v[204:207], v[108:111]
	v_mfma_f32_16x16x32_bf16 v[104:107], v[152:155], v[204:207], v[104:107]
	v_mfma_f32_16x16x32_bf16 v[92:95], v[128:131], v[212:215], v[92:95]
	v_mfma_f32_16x16x32_bf16 v[88:91], v[152:155], v[212:215], v[88:91]
	v_mfma_f32_16x16x32_bf16 v[76:79], v[128:131], v[220:223], v[76:79]
	v_mfma_f32_16x16x32_bf16 v[72:75], v[152:155], v[220:223], v[72:75]
	v_mfma_f32_16x16x32_bf16 v[124:127], v[132:135], v[200:203], v[124:127]
	v_mfma_f32_16x16x32_bf16 v[120:123], v[156:159], v[200:203], v[120:123]
	v_mfma_f32_16x16x32_bf16 v[108:111], v[132:135], v[208:211], v[108:111]
	v_mfma_f32_16x16x32_bf16 v[104:107], v[156:159], v[208:211], v[104:107]
	v_mfma_f32_16x16x32_bf16 v[92:95], v[132:135], v[216:219], v[92:95]
	v_mfma_f32_16x16x32_bf16 v[88:91], v[156:159], v[216:219], v[88:91]
	v_mfma_f32_16x16x32_bf16 v[76:79], v[132:135], v[224:227], v[76:79]
	v_mfma_f32_16x16x32_bf16 v[72:75], v[156:159], v[224:227], v[72:75]
	s_setprio 0
	s_setprio 1
	v_mfma_f32_16x16x32_bf16 v[116:119], v[180:183], v[196:199], v[116:119]
	v_mfma_f32_16x16x32_bf16 v[112:115], v[188:191], v[196:199], v[112:115]
	v_mfma_f32_16x16x32_bf16 v[100:103], v[180:183], v[204:207], v[100:103]
	v_mfma_f32_16x16x32_bf16 v[96:99], v[188:191], v[204:207], v[96:99]
	v_mfma_f32_16x16x32_bf16 v[84:87], v[180:183], v[212:215], v[84:87]
	v_mfma_f32_16x16x32_bf16 v[80:83], v[188:191], v[212:215], v[80:83]
	v_mfma_f32_16x16x32_bf16 v[68:71], v[180:183], v[220:223], v[68:71]
	v_mfma_f32_16x16x32_bf16 v[64:67], v[188:191], v[220:223], v[64:67]
	v_mfma_f32_16x16x32_bf16 v[116:119], v[184:187], v[200:203], v[116:119]
	v_mfma_f32_16x16x32_bf16 v[112:115], v[192:195], v[200:203], v[112:115]
	v_mfma_f32_16x16x32_bf16 v[100:103], v[184:187], v[208:211], v[100:103]
	v_mfma_f32_16x16x32_bf16 v[96:99], v[192:195], v[208:211], v[96:99]
	v_mfma_f32_16x16x32_bf16 v[84:87], v[184:187], v[216:219], v[84:87]
	v_mfma_f32_16x16x32_bf16 v[80:83], v[192:195], v[216:219], v[80:83]
	v_mfma_f32_16x16x32_bf16 v[68:71], v[184:187], v[224:227], v[68:71]
	v_mfma_f32_16x16x32_bf16 v[64:67], v[192:195], v[224:227], v[64:67]
	s_setprio 0
	s_barrier
	s_add_i32 vcc_hi, vcc_hi, s51
	v_lshl_add_u64 v[160:161], s[82:83], 0, v[140:141]
	s_mov_b32 m0, vcc_hi
	ds_read_b128 v[196:199], v178 offset:16384
	ds_read_b128 v[200:203], v178 offset:17408
	ds_read_b128 v[204:207], v178 offset:18432
	ds_read_b128 v[208:211], v178 offset:19456
	ds_read_b128 v[212:215], v178 offset:20480
	ds_read_b128 v[216:219], v178 offset:21504
	ds_read_b128 v[220:223], v178 offset:22528
	ds_read_b128 v[224:227], v178 offset:23552
	global_load_lds_dwordx4 v[160:161], off
	s_add_i32 m0, vcc_hi, 0x2000
	v_lshl_add_u64 v[228:229], s[82:83], 0, v[144:145]
	s_add_u32 s82, s82, s2
	s_addc_u32 s83, s83, s3
	s_add_i32 s7, s7, s51
	global_load_lds_dwordx4 v[228:229], off
	v_lshl_add_u64 v[230:231], s[82:83], 0, v[140:141]
	s_mov_b32 m0, s7
	v_lshl_add_u64 v[232:233], s[82:83], 0, v[144:145]
	global_load_lds_dwordx4 v[230:231], off
	s_add_i32 m0, s7, 0x2000
	v_lshl_add_u64 v[234:235], s[94:95], 0, v[138:139]
	global_load_lds_dwordx4 v[232:233], off
	s_mov_b32 m0, s52
	v_lshl_add_u64 v[236:237], s[94:95], 0, v[142:143]
	global_load_lds_dwordx4 v[234:235], off
	s_mov_b32 m0, s53
	s_nop 0
	global_load_lds_dwordx4 v[236:237], off
	s_waitcnt vmcnt(8)
	s_waitcnt lgkmcnt(0)
	s_barrier
	s_setprio 1
	s_waitcnt lgkmcnt(0)
	v_mfma_f32_16x16x32_bf16 v[60:63], v[128:131], v[196:199], v[60:63]
	v_mfma_f32_16x16x32_bf16 v[56:59], v[152:155], v[196:199], v[56:59]
	v_mfma_f32_16x16x32_bf16 v[44:47], v[128:131], v[204:207], v[44:47]
	v_mfma_f32_16x16x32_bf16 v[40:43], v[152:155], v[204:207], v[40:43]
	v_mfma_f32_16x16x32_bf16 v[28:31], v[128:131], v[212:215], v[28:31]
	v_mfma_f32_16x16x32_bf16 v[24:27], v[152:155], v[212:215], v[24:27]
	v_mfma_f32_16x16x32_bf16 v[12:15], v[128:131], v[220:223], v[12:15]
	v_mfma_f32_16x16x32_bf16 v[8:11], v[152:155], v[220:223], v[8:11]
	v_mfma_f32_16x16x32_bf16 v[60:63], v[132:135], v[200:203], v[60:63]
	v_mfma_f32_16x16x32_bf16 v[56:59], v[156:159], v[200:203], v[56:59]
	v_mfma_f32_16x16x32_bf16 v[44:47], v[132:135], v[208:211], v[44:47]
	v_mfma_f32_16x16x32_bf16 v[40:43], v[156:159], v[208:211], v[40:43]
	v_mfma_f32_16x16x32_bf16 v[28:31], v[132:135], v[216:219], v[28:31]
	v_mfma_f32_16x16x32_bf16 v[24:27], v[156:159], v[216:219], v[24:27]
	v_mfma_f32_16x16x32_bf16 v[12:15], v[132:135], v[224:227], v[12:15]
	v_mfma_f32_16x16x32_bf16 v[8:11], v[156:159], v[224:227], v[8:11]
	s_setprio 0
	s_setprio 1
	v_mfma_f32_16x16x32_bf16 v[52:55], v[180:183], v[196:199], v[52:55]
	v_mfma_f32_16x16x32_bf16 v[48:51], v[188:191], v[196:199], v[48:51]
	v_mfma_f32_16x16x32_bf16 v[36:39], v[180:183], v[204:207], v[36:39]
	v_mfma_f32_16x16x32_bf16 v[32:35], v[188:191], v[204:207], v[32:35]
	v_mfma_f32_16x16x32_bf16 v[20:23], v[180:183], v[212:215], v[20:23]
	v_mfma_f32_16x16x32_bf16 v[16:19], v[188:191], v[212:215], v[16:19]
	v_mfma_f32_16x16x32_bf16 v[4:7], v[180:183], v[220:223], v[4:7]
	v_mfma_f32_16x16x32_bf16 v[0:3], v[188:191], v[220:223], v[0:3]
	v_mfma_f32_16x16x32_bf16 v[52:55], v[184:187], v[200:203], v[52:55]
	v_mfma_f32_16x16x32_bf16 v[48:51], v[192:195], v[200:203], v[48:51]
	v_mfma_f32_16x16x32_bf16 v[36:39], v[184:187], v[208:211], v[36:39]
	v_mfma_f32_16x16x32_bf16 v[32:35], v[192:195], v[208:211], v[32:35]
	v_mfma_f32_16x16x32_bf16 v[20:23], v[184:187], v[216:219], v[20:23]
	v_mfma_f32_16x16x32_bf16 v[16:19], v[192:195], v[216:219], v[16:19]
	v_mfma_f32_16x16x32_bf16 v[4:7], v[184:187], v[224:227], v[4:7]
	v_mfma_f32_16x16x32_bf16 v[0:3], v[192:195], v[224:227], v[0:3]
	s_setprio 0
	s_barrier
	s_add_i32 s7, 0, 0x18000
	v_add_u32_e32 v136, s7, v176
	s_add_i32 vcc_hi, 0, 0x1c000
	ds_read_b128 v[128:131], v136
	ds_read_b128 v[132:135], v136 offset:1024
	ds_read_b128 v[152:155], v136 offset:2048
	ds_read_b128 v[156:159], v136 offset:3072
	v_add_u32_e32 v136, vcc_hi, v176
	ds_read_b128 v[180:183], v136
	ds_read_b128 v[184:187], v136 offset:1024
	ds_read_b128 v[188:191], v136 offset:2048
	ds_read_b128 v[192:195], v136 offset:3072
	s_add_u32 s82, s94, s2
	s_addc_u32 s83, s95, s3
	s_mov_b32 m0, s54
	v_lshl_add_u64 v[238:239], s[82:83], 0, v[138:139]
	ds_read_b128 v[196:199], v178 offset:32768
	ds_read_b128 v[200:203], v178 offset:33792
	ds_read_b128 v[204:207], v178 offset:34816
	ds_read_b128 v[208:211], v178 offset:35840
	ds_read_b128 v[212:215], v178 offset:36864
	ds_read_b128 v[216:219], v178 offset:37888
	ds_read_b128 v[220:223], v178 offset:38912
	ds_read_b128 v[224:227], v178 offset:39936
	global_load_lds_dwordx4 v[238:239], off
	s_mov_b32 m0, s55
	v_lshl_add_u64 v[238:239], s[82:83], 0, v[142:143]
	global_load_lds_dwordx4 v[238:239], off
	s_waitcnt vmcnt(8)
	s_waitcnt lgkmcnt(0)
	s_barrier
	s_setprio 1
	s_waitcnt lgkmcnt(0)
	v_mfma_f32_16x16x32_bf16 v[124:127], v[128:131], v[196:199], v[124:127]
	v_mfma_f32_16x16x32_bf16 v[120:123], v[152:155], v[196:199], v[120:123]
	v_mfma_f32_16x16x32_bf16 v[108:111], v[128:131], v[204:207], v[108:111]
	v_mfma_f32_16x16x32_bf16 v[104:107], v[152:155], v[204:207], v[104:107]
	v_mfma_f32_16x16x32_bf16 v[92:95], v[128:131], v[212:215], v[92:95]
	v_mfma_f32_16x16x32_bf16 v[88:91], v[152:155], v[212:215], v[88:91]
	v_mfma_f32_16x16x32_bf16 v[76:79], v[128:131], v[220:223], v[76:79]
	v_mfma_f32_16x16x32_bf16 v[72:75], v[152:155], v[220:223], v[72:75]
	v_mfma_f32_16x16x32_bf16 v[124:127], v[132:135], v[200:203], v[124:127]
	v_mfma_f32_16x16x32_bf16 v[120:123], v[156:159], v[200:203], v[120:123]
	v_mfma_f32_16x16x32_bf16 v[108:111], v[132:135], v[208:211], v[108:111]
	v_mfma_f32_16x16x32_bf16 v[104:107], v[156:159], v[208:211], v[104:107]
	v_mfma_f32_16x16x32_bf16 v[92:95], v[132:135], v[216:219], v[92:95]
	v_mfma_f32_16x16x32_bf16 v[88:91], v[156:159], v[216:219], v[88:91]
	v_mfma_f32_16x16x32_bf16 v[76:79], v[132:135], v[224:227], v[76:79]
	v_mfma_f32_16x16x32_bf16 v[72:75], v[156:159], v[224:227], v[72:75]
	s_setprio 0
	s_setprio 1
	v_mfma_f32_16x16x32_bf16 v[116:119], v[180:183], v[196:199], v[116:119]
	v_mfma_f32_16x16x32_bf16 v[112:115], v[188:191], v[196:199], v[112:115]
	v_mfma_f32_16x16x32_bf16 v[100:103], v[180:183], v[204:207], v[100:103]
	v_mfma_f32_16x16x32_bf16 v[96:99], v[188:191], v[204:207], v[96:99]
	v_mfma_f32_16x16x32_bf16 v[84:87], v[180:183], v[212:215], v[84:87]
	v_mfma_f32_16x16x32_bf16 v[80:83], v[188:191], v[212:215], v[80:83]
	v_mfma_f32_16x16x32_bf16 v[68:71], v[180:183], v[220:223], v[68:71]
	v_mfma_f32_16x16x32_bf16 v[64:67], v[188:191], v[220:223], v[64:67]
	v_mfma_f32_16x16x32_bf16 v[116:119], v[184:187], v[200:203], v[116:119]
	v_mfma_f32_16x16x32_bf16 v[112:115], v[192:195], v[200:203], v[112:115]
	v_mfma_f32_16x16x32_bf16 v[100:103], v[184:187], v[208:211], v[100:103]
	v_mfma_f32_16x16x32_bf16 v[96:99], v[192:195], v[208:211], v[96:99]
	v_mfma_f32_16x16x32_bf16 v[84:87], v[184:187], v[216:219], v[84:87]
	v_mfma_f32_16x16x32_bf16 v[80:83], v[192:195], v[216:219], v[80:83]
	v_mfma_f32_16x16x32_bf16 v[68:71], v[184:187], v[224:227], v[68:71]
	v_mfma_f32_16x16x32_bf16 v[64:67], v[192:195], v[224:227], v[64:67]
	s_setprio 0
	s_barrier
	s_add_i32 s7, s7, s51
	v_lshl_add_u64 v[160:161], v[160:161], 0, s[26:27]
	s_mov_b32 m0, s7
	ds_read_b128 v[196:199], v178 offset:49152
	ds_read_b128 v[200:203], v178 offset:50176
	ds_read_b128 v[204:207], v178 offset:51200
	ds_read_b128 v[208:211], v178 offset:52224
	ds_read_b128 v[212:215], v178 offset:53248
	ds_read_b128 v[216:219], v178 offset:54272
	ds_read_b128 v[220:223], v178 offset:55296
	ds_read_b128 v[224:227], v178 offset:56320
	global_load_lds_dwordx4 v[160:161], off
	v_lshl_add_u64 v[160:161], v[228:229], 0, s[26:27]
	s_add_i32 m0, s7, 0x2000
	s_add_i32 s7, vcc_hi, s51
	global_load_lds_dwordx4 v[160:161], off
	s_mov_b32 m0, s7
	v_lshl_add_u64 v[160:161], v[230:231], 0, s[26:27]
	global_load_lds_dwordx4 v[160:161], off
	s_add_i32 m0, s7, 0x2000
	v_lshl_add_u64 v[160:161], v[232:233], 0, s[26:27]
	global_load_lds_dwordx4 v[160:161], off
	s_mov_b32 m0, s57
	v_lshl_add_u64 v[160:161], v[234:235], 0, s[26:27]
	global_load_lds_dwordx4 v[160:161], off
	s_mov_b32 m0, s58
	v_lshl_add_u64 v[160:161], v[236:237], 0, s[26:27]
	global_load_lds_dwordx4 v[160:161], off
	s_waitcnt vmcnt(8)
	s_waitcnt lgkmcnt(0)
	s_barrier
	s_setprio 1
	s_waitcnt lgkmcnt(0)
	v_mfma_f32_16x16x32_bf16 v[60:63], v[128:131], v[196:199], v[60:63]
	v_mfma_f32_16x16x32_bf16 v[56:59], v[152:155], v[196:199], v[56:59]
	v_mfma_f32_16x16x32_bf16 v[44:47], v[128:131], v[204:207], v[44:47]
	v_mfma_f32_16x16x32_bf16 v[40:43], v[152:155], v[204:207], v[40:43]
	v_mfma_f32_16x16x32_bf16 v[28:31], v[128:131], v[212:215], v[28:31]
	v_mfma_f32_16x16x32_bf16 v[24:27], v[152:155], v[212:215], v[24:27]
	v_mfma_f32_16x16x32_bf16 v[12:15], v[128:131], v[220:223], v[12:15]
	v_mfma_f32_16x16x32_bf16 v[8:11], v[152:155], v[220:223], v[8:11]
	v_mfma_f32_16x16x32_bf16 v[60:63], v[132:135], v[200:203], v[60:63]
	v_mfma_f32_16x16x32_bf16 v[56:59], v[156:159], v[200:203], v[56:59]
	v_mfma_f32_16x16x32_bf16 v[44:47], v[132:135], v[208:211], v[44:47]
	v_mfma_f32_16x16x32_bf16 v[40:43], v[156:159], v[208:211], v[40:43]
	v_mfma_f32_16x16x32_bf16 v[28:31], v[132:135], v[216:219], v[28:31]
	v_mfma_f32_16x16x32_bf16 v[24:27], v[156:159], v[216:219], v[24:27]
	v_mfma_f32_16x16x32_bf16 v[12:15], v[132:135], v[224:227], v[12:15]
	v_mfma_f32_16x16x32_bf16 v[8:11], v[156:159], v[224:227], v[8:11]
	s_setprio 0
	s_setprio 1
	v_mfma_f32_16x16x32_bf16 v[52:55], v[180:183], v[196:199], v[52:55]
	v_mfma_f32_16x16x32_bf16 v[48:51], v[188:191], v[196:199], v[48:51]
	v_mfma_f32_16x16x32_bf16 v[36:39], v[180:183], v[204:207], v[36:39]
	v_mfma_f32_16x16x32_bf16 v[32:35], v[188:191], v[204:207], v[32:35]
	v_mfma_f32_16x16x32_bf16 v[20:23], v[180:183], v[212:215], v[20:23]
	v_mfma_f32_16x16x32_bf16 v[16:19], v[188:191], v[212:215], v[16:19]
	v_mfma_f32_16x16x32_bf16 v[4:7], v[180:183], v[220:223], v[4:7]
	v_mfma_f32_16x16x32_bf16 v[0:3], v[188:191], v[220:223], v[0:3]
	v_mfma_f32_16x16x32_bf16 v[52:55], v[184:187], v[200:203], v[52:55]
	v_mfma_f32_16x16x32_bf16 v[48:51], v[192:195], v[200:203], v[48:51]
	v_mfma_f32_16x16x32_bf16 v[36:39], v[184:187], v[208:211], v[36:39]
	v_mfma_f32_16x16x32_bf16 v[32:35], v[192:195], v[208:211], v[32:35]
	v_mfma_f32_16x16x32_bf16 v[20:23], v[184:187], v[216:219], v[20:23]
	v_mfma_f32_16x16x32_bf16 v[16:19], v[192:195], v[216:219], v[16:19]
	v_mfma_f32_16x16x32_bf16 v[4:7], v[184:187], v[224:227], v[4:7]
	v_mfma_f32_16x16x32_bf16 v[0:3], v[192:195], v[224:227], v[0:3]
	s_setprio 0
	s_barrier
	s_add_u32 s92, s92, 0x100
	s_addc_u32 s93, s93, 0
	s_add_u32 s96, s96, 0x100
	s_addc_u32 s97, s97, 0
	s_cmp_ge_u32 vcc_lo, s19
	s_mov_b32 s94, vcc_lo
	s_cbranch_scc0 .LBB0_150
